# P6: odd workgroups run gate->ple->up, even ones up->gate->ple (the three GEMMs are independent per workgroup), so HBM-bound epilogue bursts of one half overlap MFMA-bound K-loops of the other half
# speedup vs baseline: 1.0206x; 1.0138x over previous
; #define LAS __attribute__((address_space(3)))
; DI unsigned xb_add(unsigned* p, unsigned v) { return __hip_atomic_fetch_add(p, v, __ATOMIC_RELAXED, __HIP_MEMORY_SCOPE_AGENT); }
; DI unsigned xb_xcc_id() { return (unsigned)__builtin_amdgcn_s_getreg((3 << 11) | 20) & 0xFu; }
; DI XcdBarrier xcd_barrier_post(unsigned* bar, volatile LAS unsigned* st, int tid0) {
;     XcdBarrier b; b.bar = bar; b.x = xb_xcc_id(); b.st = st;
;     if (tid0 == 0) (void)xb_add(&bar[XB_XCNT(b.x)], 1u);
;     return b;
; __global__ void __launch_bounds__(512, 2) fwd_mega(Params P) {
;     cg::grid_group grid = cg::this_grid();
;     extern __shared__ __attribute__((aligned(16))) unsigned char lds[];
;     pg8::PG8_LAS_T glds = (pg8::PG8_LAS_T)lds;
;     volatile LAS unsigned* xb_words = (volatile LAS unsigned*)(glds + LDS_MISC);
;     volatile int* s_item = (volatile int*)(lds + LDS_MISC + 16);
;     const int nblk = gridDim.x, bid = blockIdx.x;
;     unsigned char* ws = P.ws;
;     const int wid_s = __builtin_amdgcn_readfirstlane((int)threadIdx.x >> 6);
;     if (threadIdx.x < 4) xb_words[threadIdx.x] = 0u;
;     __syncthreads();
;     const XcdBarrier xbar = xcd_barrier_post((unsigned*)(ws + OFF_BAR), xb_words, (int)threadIdx.x);
_Z8fwd_mega6Params:
	s_mov_b32 s98, 0
	s_mov_b32 s33, s2
	s_load_dwordx8 s[76:83], s[0:1], 0xa0
	s_load_dwordx8 s[12:19], s[0:1], 0x80
	s_load_dword s2, s[0:1], 0xc0
	s_add_u32 s4, s0, 0xb8
	v_and_b32_e32 v1, 0x3ff, v0
	s_addc_u32 s5, s1, 0
	v_readfirstlane_b32 s96, v1
	s_waitcnt lgkmcnt(0)
	v_writelane_b32 v255, s2, 0
	v_cmp_gt_u32_e32 vcc, 4, v1
	s_and_saveexec_b64 s[2:3], vcc
	v_lshl_add_u32 v2, v1, 2, 0
	v_add_u32_e32 v2, 0x25800, v2
	v_mov_b32_e32 v3, 0
	ds_write_b32 v2, v3
	s_or_b64 exec, exec, s[2:3]
	s_waitcnt lgkmcnt(0)
	s_barrier
	s_add_u32 s34, s80, 0x1d80000
	s_getreg_b32 s2, hwreg(HW_REG_XCC_ID, 0, 4)
	s_addc_u32 s35, s81, 0
	s_and_b32 s84, s2, 15
	v_cmp_eq_u32_e32 vcc, 0, v1
	s_and_saveexec_b64 s[2:3], vcc
	s_cbranch_execz .LBB0_5
	s_mov_b64 s[6:7], exec
	v_mbcnt_lo_u32_b32 v2, s6, 0
	v_mbcnt_hi_u32_b32 v2, s7, v2
	v_cmp_eq_u32_e32 vcc, 0, v2
	s_and_b64 s[8:9], exec, vcc
	s_mov_b64 exec, s[8:9]
	s_cbranch_execz .LBB0_5
	s_lshl_b32 s8, s84, 8
	s_bcnt1_i32_b64 s6, s[6:7]
	v_mov_b32_e32 v2, s8
	v_mov_b32_e32 v3, s6
	global_atomic_add v2, v3, s[34:35] offset:1024

; template <class Epi> DI void run_gemm(pg8::PG8_LAS_T lds, const bf16_t* A, const bf16_t* Bt, int N, int K, const Epi& E, const int wid_s) {
;     pg8::Gemm g{A, Bt, M_TOK, N, K}; pg8::StaticOrder S; S.init(M_TOK, N, (int)gridDim.x, (int)blockIdx.x);
;     pg8::gemm_phase<Epi, pg8::StaticOrder, true, true>(lds, g, S, E, wid_s);
; __global__ void __launch_bounds__(512, 2) fwd_mega(Params P) {
;     ...
;     { EpiUp E{(bf16_t*)(ws + OFF_FFB)}; run_gemm(glds, (const bf16_t*)(ws + OFF_H1B), (const bf16_t*)(ws + OFF_WUP), 4096, DM, E, wid_s); }
;     { EpiGate E{(bf16_t*)(ws + OFF_PG), P.in[18]}; run_gemm(glds, (const bf16_t*)(ws + OFF_H1B), (const bf16_t*)(ws + OFF_WG), DM, DM, E, wid_s); }
.Lp6_up_entry:
	s_add_u32 s4, s80, 0x4800000
	v_readlane_b32 s0, v255, 31
	s_addc_u32 s5, s81, 0
	s_lshl_b32 s0, s0, 5
	s_and_b32 s36, s0, 0x60
	s_lshl_b32 s37, s36, 7
	s_cmpk_gt_i32 s33, 0x3ff
	s_waitcnt lgkmcnt(0)
	s_barrier
	v_mbcnt_lo_u32_b32 v8, -1, 0
	v_mbcnt_hi_u32_b32 v8, -1, v8
	s_cbranch_scc1 .LBB0_830
	s_cmp_eq_u32 s98, 0
	s_cbranch_scc0 .Lp6_up_go
	s_bitcmp1_b32 s33, 0
	s_cbranch_scc0 .Lp6_up_go
	s_mov_b32 s98, 1
	s_branch .LBB0_830
.Lp6_up_go:
	s_ashr_i32 s28, s33, 31
	s_lshr_b32 s0, s28, 29
	s_add_i32 s3, s33, s0
	s_and_b32 s0, s3, -8
	s_sub_i32 s6, s33, s0
	s_cmp_gt_i32 s6, -1
	s_cbranch_scc0 .LBB0_809
	s_lshl_b32 s2, s6, 7
	s_cbranch_execz .LBB0_810
	s_branch .LBB0_811

; __global__ void __launch_bounds__(512, 2) fwd_mega(Params P) {
;     ...
;     { EpiUp E{(bf16_t*)(ws + OFF_FFB)}; run_gemm(glds, (const bf16_t*)(ws + OFF_H1B), (const bf16_t*)(ws + OFF_WUP), 4096, DM, E, wid_s); }
;     { EpiGate E{(bf16_t*)(ws + OFF_PG), P.in[18]}; run_gemm(glds, (const bf16_t*)(ws + OFF_H1B), (const bf16_t*)(ws + OFF_WG), DM, DM, E, wid_s); }
;     { EpiPle E{(bf16_t*)(ws + OFF_PG)}; run_gemm(glds, (const bf16_t*)(ws + OFF_PB), (const bf16_t*)(ws + OFF_WPLE), DM, 256, E, wid_s); }
.LBB0_830:
	s_cmp_eq_u32 s98, 2
	s_cbranch_scc1 .Lp6_to_b7
	s_add_u32 s6, s80, 0xc800000
	v_cndmask_b32_e64 v0, 0, 1, s[8:9]
	s_addc_u32 s7, s81, 0
	v_cmp_ne_u32_e64 s[0:1], 1, v0
	s_andn2_b64 vcc, exec, s[8:9]
	v_mbcnt_lo_u32_b32 v8, -1, 0
	v_mbcnt_hi_u32_b32 v8, -1, v8
	s_cbranch_vccnz .LBB0_854
	s_ashr_i32 s30, s33, 31
	s_lshr_b32 s2, s30, 29
	s_add_i32 s9, s33, s2
	s_and_b32 s2, s9, -8
	s_sub_i32 s10, s33, s2
	s_cmp_gt_i32 s10, -1
	s_cbranch_scc0 .LBB0_833
	s_lshl_b32 s8, s10, 5
	s_cbranch_execz .LBB0_834
	s_branch .LBB0_835

; __global__ void __launch_bounds__(512, 2) fwd_mega(Params P) {
;     ...
;     { EpiUp E{(bf16_t*)(ws + OFF_FFB)}; run_gemm(glds, (const bf16_t*)(ws + OFF_H1B), (const bf16_t*)(ws + OFF_WUP), 4096, DM, E, wid_s); }
;     { EpiGate E{(bf16_t*)(ws + OFF_PG), P.in[18]}; run_gemm(glds, (const bf16_t*)(ws + OFF_H1B), (const bf16_t*)(ws + OFF_WG), DM, DM, E, wid_s); }
;     { EpiPle E{(bf16_t*)(ws + OFF_PG)}; run_gemm(glds, (const bf16_t*)(ws + OFF_PB), (const bf16_t*)(ws + OFF_WPLE), DM, 256, E, wid_s); }
;     xcd_barrier(xbar, wid_s);
.LBB0_876:
	s_cmp_eq_u32 s98, 1
	s_cbranch_scc0 .Lp6_b7_go
	s_mov_b32 s98, 2
	s_branch .Lp6_up_entry
.Lp6_to_b7:
	s_add_u32 s6, s80, 0xc800000
	s_addc_u32 s7, s81, 0
	s_cmpk_gt_i32 s33, 0xff
	s_cselect_b64 s[0:1], -1, 0
	s_mov_b32 s98, 3
